# grid barrier: 16 arrival-counter loads batched; L1 invalidate moved from barrier exit to barrier entry (off the critical path for all but the last arriver)
# speedup vs baseline: 1.1033x; 1.0189x over previous
.LBB0_916:
	buffer_inv sc1
	s_add_i32 s11, 0, 0x12ff0
	s_mov_b64 s[2:3], src_shared_base
	s_cmp_lg_u32 s11, -1
	s_cselect_b32 s2, s11, 0
	s_cselect_b32 s4, s3, 0
	s_add_i32 s10, 0, 0x12ff4
	s_cmp_lg_u32 s10, -1
	v_mov_b32_e32 v2, s2
	v_mov_b32_e32 v3, s4
	s_cselect_b32 s2, s10, 0
	s_cselect_b32 s3, s3, 0
	s_waitcnt vmcnt(0) expcnt(0) lgkmcnt(0)
	flat_load_dword v2, v[2:3] sc0 sc1
	s_waitcnt vmcnt(0)
	v_mov_b32_e32 v4, s2
	v_mov_b32_e32 v5, s3
	flat_load_dword v0, v[4:5] sc0 sc1
	s_waitcnt vmcnt(0) lgkmcnt(0)
	v_cmp_eq_u32_e32 vcc, 0, v2
	s_and_saveexec_b64 s[2:3], vcc
	s_cbranch_execz .LBB0_931
	v_readlane_b32 s6, v250, 4
	v_readlane_b32 s7, v250, 5
	s_load_dwordx2 s[4:5], s[6:7], 0x0
	s_nop 0
	s_load_dword s6, s[6:7], 0x8
	s_mov_b32 s13, 1
	s_waitcnt lgkmcnt(0)
	s_mul_i32 s12, s5, s4
	s_mul_i32 s12, s12, s6
	s_branch .LBB0_919

.LBB0_919:
	s_mov_b64 s[6:7], -1
	v_readlane_b32 s4, v250, 30
	v_readlane_b32 s5, v250, 31
	s_nop 4
	global_load_dword v0, v1, s[4:5] sc1
	v_readlane_b32 s4, v250, 32
	v_readlane_b32 s5, v250, 33
	s_nop 4
	global_load_dword v2, v1, s[4:5] sc1
	v_readlane_b32 s4, v250, 34
	v_readlane_b32 s5, v250, 35
	s_nop 4
	global_load_dword v3, v1, s[4:5] sc1
	v_readlane_b32 s4, v250, 36
	v_readlane_b32 s5, v250, 37
	s_nop 4
	global_load_dword v4, v1, s[4:5] sc1
	v_readlane_b32 s4, v250, 38
	v_readlane_b32 s5, v250, 39
	s_nop 4
	global_load_dword v5, v1, s[4:5] sc1
	v_readlane_b32 s4, v250, 40
	v_readlane_b32 s5, v250, 41
	s_nop 4
	global_load_dword v6, v1, s[4:5] sc1
	v_readlane_b32 s4, v250, 42
	v_readlane_b32 s5, v250, 43
	s_nop 4
	global_load_dword v7, v1, s[4:5] sc1
	v_readlane_b32 s4, v250, 44
	v_readlane_b32 s5, v250, 45
	s_nop 4
	global_load_dword v8, v1, s[4:5] sc1
	v_readlane_b32 s4, v250, 46
	v_readlane_b32 s5, v250, 47
	s_nop 4
	global_load_dword v9, v1, s[4:5] sc1
	v_readlane_b32 s4, v250, 48
	v_readlane_b32 s5, v250, 49
	s_nop 4
	global_load_dword v10, v1, s[4:5] sc1
	v_readlane_b32 s4, v250, 50
	v_readlane_b32 s5, v250, 51
	s_nop 4
	global_load_dword v11, v1, s[4:5] sc1
	v_readlane_b32 s4, v250, 52
	v_readlane_b32 s5, v250, 53
	s_nop 4
	global_load_dword v12, v1, s[4:5] sc1
	v_readlane_b32 s4, v250, 54
	v_readlane_b32 s5, v250, 55
	s_nop 4
	global_load_dword v13, v1, s[4:5] sc1
	v_readlane_b32 s4, v250, 56
	v_readlane_b32 s5, v250, 57
	s_nop 4
	global_load_dword v14, v1, s[4:5] sc1
	v_readlane_b32 s4, v250, 58
	v_readlane_b32 s5, v250, 59
	s_nop 4
	global_load_dword v15, v1, s[4:5] sc1
	v_readlane_b32 s4, v250, 60
	v_readlane_b32 s5, v250, 61
	s_nop 4
	global_load_dword v16, v1, s[4:5] sc1
	s_mov_b64 s[4:5], -1
	s_waitcnt vmcnt(0)
	v_add_u32_e32 v17, v2, v0
	v_add_u32_e32 v17, v17, v3
	v_add_u32_e32 v17, v17, v4
	v_add_u32_e32 v17, v17, v5
	v_add_u32_e32 v17, v17, v6
	v_add_u32_e32 v17, v17, v7
	v_add_u32_e32 v17, v17, v8
	v_add_u32_e32 v17, v17, v9
	v_add_u32_e32 v17, v17, v10
	v_add_u32_e32 v17, v17, v11
	v_add_u32_e32 v17, v17, v12
	v_add_u32_e32 v17, v17, v13
	v_add_u32_e32 v17, v17, v14
	v_add_u32_e32 v17, v17, v15
	v_add_u32_e32 v17, v17, v16
	v_cmp_eq_u32_e32 vcc, s12, v17
	s_cbranch_vccnz .LBB0_918
	s_and_b32 s4, s13, 0xff
	s_cmp_eq_u32 s4, 0
	s_mov_b64 s[4:5], -1
	s_mov_b64 s[8:9], -1
	s_sleep 1
	s_cbranch_scc1 .LBB0_923
	s_and_b64 vcc, exec, s[8:9]
	s_cbranch_vccz .LBB0_918

.LBB0_946:
	s_or_b64 exec, exec, s[4:5]
	s_waitcnt vmcnt(0) lgkmcnt(0)
.LBB0_947:
	s_andn2_saveexec_b64 s[2:3], s[2:3]
	s_cbranch_execnz .LBB0_948
	s_getpc_b64 s[98:99]

.LBB0_964:
	s_or_b64 exec, exec, s[2:3]
	s_mov_b64 s[2:3], exec
	v_mbcnt_lo_u32_b32 v0, s2, 0
	v_mbcnt_hi_u32_b32 v0, s3, v0
	v_cmp_eq_u32_e32 vcc, 0, v0
	s_waitcnt vmcnt(0)
	s_and_saveexec_b64 s[4:5], vcc
	s_cbranch_execnz .LBB0_965
	s_getpc_b64 s[98:99]
